# GEMM K-loops: M0 wait state supplied by a moved ds_read instead of s_nop, pre-barrier waits merged, post-barrier no-op lgkmcnt wait dropped
# baseline (speedup 1.0000x reference)
.LBB0_120:
	ds_read_b128 v[130:133], v245
	ds_read_b128 v[134:137], v245 offset:1024
	ds_read_b128 v[138:141], v245 offset:2048
	ds_read_b128 v[142:145], v245 offset:3072
	s_waitcnt vmcnt(0)
	ds_read_b128 v[146:149], v246
	ds_read_b128 v[150:153], v246 offset:1024
	ds_read_b128 v[154:157], v246 offset:2048
	ds_read_b128 v[158:161], v246 offset:3072
	s_add_u32 s16, s6, 0xfffc0080
	s_addc_u32 s17, s7, -1
	s_cmp_eq_u32 s40, 12
	s_cselect_b32 s79, s1, s17
	s_cselect_b32 s78, s2, s16
	s_cselect_b32 s17, s3, s37
	s_cselect_b32 s16, s9, s35
	s_add_i32 m0, s71, 0xc000
	ds_read_b128 v[162:165], v247
	ds_read_b128 v[166:169], v247 offset:1024
	ds_read_b128 v[170:173], v247 offset:2048
	ds_read_b128 v[174:177], v247 offset:3072
	ds_read_b128 v[178:181], v247 offset:4096
	ds_read_b128 v[182:185], v247 offset:5120
	ds_read_b128 v[186:189], v247 offset:6144
	global_load_lds_dwordx4 v226, s[6:7]
	s_add_i32 m0, s71, 0xe000
	ds_read_b128 v[190:193], v247 offset:7168
	global_load_lds_dwordx4 v228, s[6:7]
	s_waitcnt vmcnt(8) lgkmcnt(0)
	s_barrier
	s_setprio 1
	v_mfma_f32_16x16x32_bf16 v[126:129], v[130:133], v[162:165], v[126:129]
	v_mfma_f32_16x16x32_bf16 v[122:125], v[138:141], v[162:165], v[122:125]
	v_mfma_f32_16x16x32_bf16 v[110:113], v[130:133], v[170:173], v[110:113]
	v_mfma_f32_16x16x32_bf16 v[106:109], v[138:141], v[170:173], v[106:109]
	v_mfma_f32_16x16x32_bf16 v[94:97], v[130:133], v[178:181], v[94:97]
	v_mfma_f32_16x16x32_bf16 v[90:93], v[138:141], v[178:181], v[90:93]
	v_mfma_f32_16x16x32_bf16 v[78:81], v[130:133], v[186:189], v[78:81]
	v_mfma_f32_16x16x32_bf16 v[74:77], v[138:141], v[186:189], v[74:77]
	v_mfma_f32_16x16x32_bf16 v[126:129], v[134:137], v[166:169], v[126:129]
	v_mfma_f32_16x16x32_bf16 v[122:125], v[142:145], v[166:169], v[122:125]
	v_mfma_f32_16x16x32_bf16 v[110:113], v[134:137], v[174:177], v[110:113]
	v_mfma_f32_16x16x32_bf16 v[106:109], v[142:145], v[174:177], v[106:109]
	v_mfma_f32_16x16x32_bf16 v[94:97], v[134:137], v[182:185], v[94:97]
	v_mfma_f32_16x16x32_bf16 v[90:93], v[142:145], v[182:185], v[90:93]
	v_mfma_f32_16x16x32_bf16 v[78:81], v[134:137], v[190:193], v[78:81]
	v_mfma_f32_16x16x32_bf16 v[74:77], v[142:145], v[190:193], v[74:77]
	s_setprio 0
	s_setprio 1
	v_mfma_f32_16x16x32_bf16 v[118:121], v[146:149], v[162:165], v[118:121]
	v_mfma_f32_16x16x32_bf16 v[114:117], v[154:157], v[162:165], v[114:117]
	v_mfma_f32_16x16x32_bf16 v[102:105], v[146:149], v[170:173], v[102:105]
	v_mfma_f32_16x16x32_bf16 v[98:101], v[154:157], v[170:173], v[98:101]
	v_mfma_f32_16x16x32_bf16 v[86:89], v[146:149], v[178:181], v[86:89]
	v_mfma_f32_16x16x32_bf16 v[82:85], v[154:157], v[178:181], v[82:85]
	v_mfma_f32_16x16x32_bf16 v[70:73], v[146:149], v[186:189], v[70:73]
	v_mfma_f32_16x16x32_bf16 v[66:69], v[154:157], v[186:189], v[66:69]
	v_mfma_f32_16x16x32_bf16 v[118:121], v[150:153], v[166:169], v[118:121]
	v_mfma_f32_16x16x32_bf16 v[114:117], v[158:161], v[166:169], v[114:117]
	v_mfma_f32_16x16x32_bf16 v[102:105], v[150:153], v[174:177], v[102:105]
	v_mfma_f32_16x16x32_bf16 v[98:101], v[158:161], v[174:177], v[98:101]
	v_mfma_f32_16x16x32_bf16 v[86:89], v[150:153], v[182:185], v[86:89]
	v_mfma_f32_16x16x32_bf16 v[82:85], v[158:161], v[182:185], v[82:85]
	v_mfma_f32_16x16x32_bf16 v[70:73], v[150:153], v[190:193], v[70:73]
	v_mfma_f32_16x16x32_bf16 v[66:69], v[158:161], v[190:193], v[66:69]
	s_setprio 0
	s_barrier
	s_add_i32 s41, s12, s39
	s_mov_b32 m0, s41
	ds_read_b128 v[162:165], v247 offset:16384
	ds_read_b128 v[166:169], v247 offset:17408
	ds_read_b128 v[170:173], v247 offset:18432
	ds_read_b128 v[174:177], v247 offset:19456
	global_load_lds_dwordx4 v212, s[16:17]
	s_add_i32 m0, s41, 0x2000
	s_add_u32 s42, s16, 0x40000
	s_addc_u32 s43, s17, 0
	s_add_i32 s41, s13, s39
	global_load_lds_dwordx4 v216, s[16:17]
	s_mov_b32 m0, s41
	ds_read_b128 v[190:193], v247 offset:23552
	global_load_lds_dwordx4 v212, s[42:43]
	s_add_i32 m0, s41, 0x2000
	ds_read_b128 v[186:189], v247 offset:22528
	global_load_lds_dwordx4 v216, s[42:43]
	s_mov_b32 m0, s71
	ds_read_b128 v[182:185], v247 offset:21504
	global_load_lds_dwordx4 v210, s[78:79]
	s_mov_b32 m0, s20
	ds_read_b128 v[178:181], v247 offset:20480
	global_load_lds_dwordx4 v214, s[78:79]
	s_waitcnt vmcnt(8) lgkmcnt(0)
	s_barrier
	s_setprio 1
	v_mfma_f32_16x16x32_bf16 v[62:65], v[130:133], v[162:165], v[62:65]
	v_mfma_f32_16x16x32_bf16 v[58:61], v[138:141], v[162:165], v[58:61]
	v_mfma_f32_16x16x32_bf16 v[46:49], v[130:133], v[170:173], v[46:49]
	v_mfma_f32_16x16x32_bf16 v[42:45], v[138:141], v[170:173], v[42:45]
	v_mfma_f32_16x16x32_bf16 v[30:33], v[130:133], v[178:181], v[30:33]
	v_mfma_f32_16x16x32_bf16 v[26:29], v[138:141], v[178:181], v[26:29]
	v_mfma_f32_16x16x32_bf16 v[14:17], v[130:133], v[186:189], v[14:17]
	v_mfma_f32_16x16x32_bf16 v[10:13], v[138:141], v[186:189], v[10:13]
	v_mfma_f32_16x16x32_bf16 v[62:65], v[134:137], v[166:169], v[62:65]
	v_mfma_f32_16x16x32_bf16 v[58:61], v[142:145], v[166:169], v[58:61]
	v_mfma_f32_16x16x32_bf16 v[46:49], v[134:137], v[174:177], v[46:49]
	v_mfma_f32_16x16x32_bf16 v[42:45], v[142:145], v[174:177], v[42:45]
	v_mfma_f32_16x16x32_bf16 v[30:33], v[134:137], v[182:185], v[30:33]
	v_mfma_f32_16x16x32_bf16 v[26:29], v[142:145], v[182:185], v[26:29]
	v_mfma_f32_16x16x32_bf16 v[14:17], v[134:137], v[190:193], v[14:17]
	v_mfma_f32_16x16x32_bf16 v[10:13], v[142:145], v[190:193], v[10:13]
	s_setprio 0
	s_setprio 1
	v_mfma_f32_16x16x32_bf16 v[54:57], v[146:149], v[162:165], v[54:57]
	v_mfma_f32_16x16x32_bf16 v[50:53], v[154:157], v[162:165], v[50:53]
	v_mfma_f32_16x16x32_bf16 v[38:41], v[146:149], v[170:173], v[38:41]
	v_mfma_f32_16x16x32_bf16 v[34:37], v[154:157], v[170:173], v[34:37]
	v_mfma_f32_16x16x32_bf16 v[22:25], v[146:149], v[178:181], v[22:25]
	v_mfma_f32_16x16x32_bf16 v[18:21], v[154:157], v[178:181], v[18:21]
	v_mfma_f32_16x16x32_bf16 v[6:9], v[146:149], v[186:189], v[6:9]
	v_mfma_f32_16x16x32_bf16 v[2:5], v[154:157], v[186:189], v[2:5]
	v_mfma_f32_16x16x32_bf16 v[54:57], v[150:153], v[166:169], v[54:57]
	v_mfma_f32_16x16x32_bf16 v[50:53], v[158:161], v[166:169], v[50:53]
	v_mfma_f32_16x16x32_bf16 v[38:41], v[150:153], v[174:177], v[38:41]
	v_mfma_f32_16x16x32_bf16 v[34:37], v[158:161], v[174:177], v[34:37]
	v_mfma_f32_16x16x32_bf16 v[22:25], v[150:153], v[182:185], v[22:25]
	v_mfma_f32_16x16x32_bf16 v[18:21], v[158:161], v[182:185], v[18:21]
	v_mfma_f32_16x16x32_bf16 v[6:9], v[150:153], v[190:193], v[6:9]
	v_mfma_f32_16x16x32_bf16 v[2:5], v[158:161], v[190:193], v[2:5]
	s_setprio 0
	s_barrier
	s_add_i32 s41, 0, 0x18000
	s_add_i32 s44, 0, 0x1c000
	v_add_u32_e32 v142, s41, v223
	v_add_u32_e32 v158, s44, v223
	ds_read_b128 v[130:133], v142
	ds_read_b128 v[134:137], v142 offset:1024
	ds_read_b128 v[138:141], v142 offset:2048
	ds_read_b128 v[142:145], v142 offset:3072
	ds_read_b128 v[146:149], v158
	ds_read_b128 v[150:153], v158 offset:1024
	ds_read_b128 v[154:157], v158 offset:2048
	ds_read_b128 v[158:161], v158 offset:3072
	s_add_u32 s42, s78, 0x40000
	s_addc_u32 s43, s79, 0
	s_mov_b32 m0, s21
	ds_read_b128 v[162:165], v247 offset:32768
	ds_read_b128 v[166:169], v247 offset:33792
	ds_read_b128 v[170:173], v247 offset:34816
	ds_read_b128 v[174:177], v247 offset:35840
	ds_read_b128 v[178:181], v247 offset:36864
	ds_read_b128 v[182:185], v247 offset:37888
	ds_read_b128 v[186:189], v247 offset:38912
	global_load_lds_dwordx4 v210, s[42:43]
	s_mov_b32 m0, s22
	ds_read_b128 v[190:193], v247 offset:39936
	global_load_lds_dwordx4 v214, s[42:43]
	s_waitcnt vmcnt(8) lgkmcnt(0)
	s_barrier
	s_setprio 1
	v_mfma_f32_16x16x32_bf16 v[126:129], v[130:133], v[162:165], v[126:129]
	v_mfma_f32_16x16x32_bf16 v[122:125], v[138:141], v[162:165], v[122:125]
	v_mfma_f32_16x16x32_bf16 v[110:113], v[130:133], v[170:173], v[110:113]
	v_mfma_f32_16x16x32_bf16 v[106:109], v[138:141], v[170:173], v[106:109]
	v_mfma_f32_16x16x32_bf16 v[94:97], v[130:133], v[178:181], v[94:97]
	v_mfma_f32_16x16x32_bf16 v[90:93], v[138:141], v[178:181], v[90:93]
	v_mfma_f32_16x16x32_bf16 v[78:81], v[130:133], v[186:189], v[78:81]
	v_mfma_f32_16x16x32_bf16 v[74:77], v[138:141], v[186:189], v[74:77]
	v_mfma_f32_16x16x32_bf16 v[126:129], v[134:137], v[166:169], v[126:129]
	v_mfma_f32_16x16x32_bf16 v[122:125], v[142:145], v[166:169], v[122:125]
	v_mfma_f32_16x16x32_bf16 v[110:113], v[134:137], v[174:177], v[110:113]
	v_mfma_f32_16x16x32_bf16 v[106:109], v[142:145], v[174:177], v[106:109]
	v_mfma_f32_16x16x32_bf16 v[94:97], v[134:137], v[182:185], v[94:97]
	v_mfma_f32_16x16x32_bf16 v[90:93], v[142:145], v[182:185], v[90:93]
	v_mfma_f32_16x16x32_bf16 v[78:81], v[134:137], v[190:193], v[78:81]
	v_mfma_f32_16x16x32_bf16 v[74:77], v[142:145], v[190:193], v[74:77]
	s_setprio 0
	s_setprio 1
	v_mfma_f32_16x16x32_bf16 v[118:121], v[146:149], v[162:165], v[118:121]
	v_mfma_f32_16x16x32_bf16 v[114:117], v[154:157], v[162:165], v[114:117]
	v_mfma_f32_16x16x32_bf16 v[102:105], v[146:149], v[170:173], v[102:105]
	v_mfma_f32_16x16x32_bf16 v[98:101], v[154:157], v[170:173], v[98:101]
	v_mfma_f32_16x16x32_bf16 v[86:89], v[146:149], v[178:181], v[86:89]
	v_mfma_f32_16x16x32_bf16 v[82:85], v[154:157], v[178:181], v[82:85]
	v_mfma_f32_16x16x32_bf16 v[70:73], v[146:149], v[186:189], v[70:73]
	v_mfma_f32_16x16x32_bf16 v[66:69], v[154:157], v[186:189], v[66:69]
	v_mfma_f32_16x16x32_bf16 v[118:121], v[150:153], v[166:169], v[118:121]
	v_mfma_f32_16x16x32_bf16 v[114:117], v[158:161], v[166:169], v[114:117]
	v_mfma_f32_16x16x32_bf16 v[102:105], v[150:153], v[174:177], v[102:105]
	v_mfma_f32_16x16x32_bf16 v[98:101], v[158:161], v[174:177], v[98:101]
	v_mfma_f32_16x16x32_bf16 v[86:89], v[150:153], v[182:185], v[86:89]
	v_mfma_f32_16x16x32_bf16 v[82:85], v[158:161], v[182:185], v[82:85]
	v_mfma_f32_16x16x32_bf16 v[70:73], v[150:153], v[190:193], v[70:73]
	v_mfma_f32_16x16x32_bf16 v[66:69], v[158:161], v[190:193], v[66:69]
	s_setprio 0
	s_barrier
	s_add_i32 s41, s41, s39
	s_add_i32 m0, s41, 0xffffff80
	ds_read_b128 v[162:165], v247 offset:49152
	ds_read_b128 v[166:169], v247 offset:50176
	ds_read_b128 v[170:173], v247 offset:51200
	ds_read_b128 v[174:177], v247 offset:52224
	global_load_lds_dwordx4 v212, s[16:17] offset:128
	s_add_i32 m0, s41, 0x1f80
	s_add_i32 s41, s44, s39
	global_load_lds_dwordx4 v216, s[16:17] offset:128
	s_add_u32 s16, s16, 0x40080
	s_addc_u32 s17, s17, 0
	s_mov_b32 m0, s41
	ds_read_b128 v[190:193], v247 offset:56320
	global_load_lds_dwordx4 v212, s[16:17]
	s_add_i32 m0, s41, 0x2000
	ds_read_b128 v[186:189], v247 offset:55296
	global_load_lds_dwordx4 v216, s[16:17]
	s_add_i32 m0, s14, 0xffffff80
	ds_read_b128 v[182:185], v247 offset:54272
	global_load_lds_dwordx4 v210, s[78:79] offset:128
	s_add_i32 m0, s15, 0xffffff80
	ds_read_b128 v[178:181], v247 offset:53248
	global_load_lds_dwordx4 v214, s[78:79] offset:128
	s_waitcnt vmcnt(8) lgkmcnt(0)
	s_barrier
	s_setprio 1
	v_mfma_f32_16x16x32_bf16 v[62:65], v[130:133], v[162:165], v[62:65]
	v_mfma_f32_16x16x32_bf16 v[58:61], v[138:141], v[162:165], v[58:61]
	v_mfma_f32_16x16x32_bf16 v[46:49], v[130:133], v[170:173], v[46:49]
	v_mfma_f32_16x16x32_bf16 v[42:45], v[138:141], v[170:173], v[42:45]
	v_mfma_f32_16x16x32_bf16 v[30:33], v[130:133], v[178:181], v[30:33]
	v_mfma_f32_16x16x32_bf16 v[26:29], v[138:141], v[178:181], v[26:29]
	v_mfma_f32_16x16x32_bf16 v[14:17], v[130:133], v[186:189], v[14:17]
	v_mfma_f32_16x16x32_bf16 v[10:13], v[138:141], v[186:189], v[10:13]
	v_mfma_f32_16x16x32_bf16 v[62:65], v[134:137], v[166:169], v[62:65]
	v_mfma_f32_16x16x32_bf16 v[58:61], v[142:145], v[166:169], v[58:61]
	v_mfma_f32_16x16x32_bf16 v[46:49], v[134:137], v[174:177], v[46:49]
	v_mfma_f32_16x16x32_bf16 v[42:45], v[142:145], v[174:177], v[42:45]
	v_mfma_f32_16x16x32_bf16 v[30:33], v[134:137], v[182:185], v[30:33]
	v_mfma_f32_16x16x32_bf16 v[26:29], v[142:145], v[182:185], v[26:29]
	v_mfma_f32_16x16x32_bf16 v[14:17], v[134:137], v[190:193], v[14:17]
	v_mfma_f32_16x16x32_bf16 v[10:13], v[142:145], v[190:193], v[10:13]
	s_setprio 0
	s_setprio 1
	v_mfma_f32_16x16x32_bf16 v[54:57], v[146:149], v[162:165], v[54:57]
	v_mfma_f32_16x16x32_bf16 v[50:53], v[154:157], v[162:165], v[50:53]
	v_mfma_f32_16x16x32_bf16 v[38:41], v[146:149], v[170:173], v[38:41]
	v_mfma_f32_16x16x32_bf16 v[34:37], v[154:157], v[170:173], v[34:37]
	v_mfma_f32_16x16x32_bf16 v[22:25], v[146:149], v[178:181], v[22:25]
	v_mfma_f32_16x16x32_bf16 v[18:21], v[154:157], v[178:181], v[18:21]
	v_mfma_f32_16x16x32_bf16 v[6:9], v[146:149], v[186:189], v[6:9]
	v_mfma_f32_16x16x32_bf16 v[2:5], v[154:157], v[186:189], v[2:5]
	v_mfma_f32_16x16x32_bf16 v[54:57], v[150:153], v[166:169], v[54:57]
	v_mfma_f32_16x16x32_bf16 v[50:53], v[158:161], v[166:169], v[50:53]
	v_mfma_f32_16x16x32_bf16 v[38:41], v[150:153], v[174:177], v[38:41]
	v_mfma_f32_16x16x32_bf16 v[34:37], v[158:161], v[174:177], v[34:37]
	v_mfma_f32_16x16x32_bf16 v[22:25], v[150:153], v[182:185], v[22:25]
	v_mfma_f32_16x16x32_bf16 v[18:21], v[158:161], v[182:185], v[18:21]
	v_mfma_f32_16x16x32_bf16 v[6:9], v[150:153], v[190:193], v[6:9]
	v_mfma_f32_16x16x32_bf16 v[2:5], v[158:161], v[190:193], v[2:5]
	s_setprio 0
	s_barrier
	s_add_i32 s40, s40, 2
	s_add_u32 s6, s6, 0x100
	s_addc_u32 s7, s7, 0
	s_add_u32 s35, s35, 0x100
	s_addc_u32 s37, s37, 0
	s_cmp_gt_u32 s40, 13
	s_cbranch_scc0 .LBB0_120
	s_and_b64 vcc, exec, s[48:49]
	s_cbranch_vccz .LBB0_123
	s_barrier

.LBB0_518:
	ds_read_b128 v[148:151], v143
	ds_read_b128 v[152:155], v143 offset:1024
	ds_read_b128 v[158:161], v143 offset:2048
	ds_read_b128 v[162:165], v143 offset:3072
	ds_read_b128 v[166:169], v144
	ds_read_b128 v[170:173], v144 offset:1024
	ds_read_b128 v[174:177], v144 offset:2048
	ds_read_b128 v[178:181], v144 offset:3072
	s_add_u32 s16, s8, s10
	s_addc_u32 s17, s9, s11
	s_add_u32 s16, s16, 0x1000100
	s_addc_u32 s17, s17, 0
	s_add_u32 s44, s30, s10
	s_addc_u32 s45, s31, s11
	s_cmpk_eq_i32 s10, 0x700
	s_cselect_b32 s29, s7, s17
	s_cselect_b32 s28, s6, s16
	s_cselect_b32 s17, s5, s45
	s_cselect_b32 s16, s4, s44
	s_mov_b32 m0, s34
	v_lshl_add_u64 v[214:215], v[138:139], 0, s[10:11]
	ds_read_b128 v[182:185], v145
	ds_read_b128 v[186:189], v145 offset:1024
	ds_read_b128 v[190:193], v145 offset:2048
	ds_read_b128 v[194:197], v145 offset:3072
	ds_read_b128 v[198:201], v145 offset:4096
	ds_read_b128 v[202:205], v145 offset:5120
	ds_read_b128 v[206:209], v145 offset:6144
	global_load_lds_dwordx4 v[214:215], off
	v_lshl_add_u64 v[214:215], v[140:141], 0, s[10:11]
	s_mov_b32 m0, s35
	ds_read_b128 v[210:213], v145 offset:7168
	global_load_lds_dwordx4 v[214:215], off
	s_waitcnt vmcnt(8) lgkmcnt(0)
	s_barrier
	s_setprio 1
	v_mfma_f32_16x16x32_bf16 v[126:129], v[148:151], v[182:185], v[126:129]
	v_mfma_f32_16x16x32_bf16 v[122:125], v[158:161], v[182:185], v[122:125]
	v_mfma_f32_16x16x32_bf16 v[110:113], v[148:151], v[190:193], v[110:113]
	v_mfma_f32_16x16x32_bf16 v[106:109], v[158:161], v[190:193], v[106:109]
	v_mfma_f32_16x16x32_bf16 v[94:97], v[148:151], v[198:201], v[94:97]
	v_mfma_f32_16x16x32_bf16 v[90:93], v[158:161], v[198:201], v[90:93]
	v_mfma_f32_16x16x32_bf16 v[78:81], v[148:151], v[206:209], v[78:81]
	v_mfma_f32_16x16x32_bf16 v[74:77], v[158:161], v[206:209], v[74:77]
	v_mfma_f32_16x16x32_bf16 v[126:129], v[152:155], v[186:189], v[126:129]
	v_mfma_f32_16x16x32_bf16 v[122:125], v[162:165], v[186:189], v[122:125]
	v_mfma_f32_16x16x32_bf16 v[110:113], v[152:155], v[194:197], v[110:113]
	v_mfma_f32_16x16x32_bf16 v[106:109], v[162:165], v[194:197], v[106:109]
	v_mfma_f32_16x16x32_bf16 v[94:97], v[152:155], v[202:205], v[94:97]
	v_mfma_f32_16x16x32_bf16 v[90:93], v[162:165], v[202:205], v[90:93]
	v_mfma_f32_16x16x32_bf16 v[78:81], v[152:155], v[210:213], v[78:81]
	v_mfma_f32_16x16x32_bf16 v[74:77], v[162:165], v[210:213], v[74:77]
	s_setprio 0
	s_setprio 1
	v_mfma_f32_16x16x32_bf16 v[118:121], v[166:169], v[182:185], v[118:121]
	v_mfma_f32_16x16x32_bf16 v[114:117], v[174:177], v[182:185], v[114:117]
	v_mfma_f32_16x16x32_bf16 v[102:105], v[166:169], v[190:193], v[102:105]
	v_mfma_f32_16x16x32_bf16 v[98:101], v[174:177], v[190:193], v[98:101]
	v_mfma_f32_16x16x32_bf16 v[86:89], v[166:169], v[198:201], v[86:89]
	v_mfma_f32_16x16x32_bf16 v[82:85], v[174:177], v[198:201], v[82:85]
	v_mfma_f32_16x16x32_bf16 v[70:73], v[166:169], v[206:209], v[70:73]
	v_mfma_f32_16x16x32_bf16 v[66:69], v[174:177], v[206:209], v[66:69]
	v_mfma_f32_16x16x32_bf16 v[118:121], v[170:173], v[186:189], v[118:121]
	v_mfma_f32_16x16x32_bf16 v[114:117], v[178:181], v[186:189], v[114:117]
	v_mfma_f32_16x16x32_bf16 v[102:105], v[170:173], v[194:197], v[102:105]
	v_mfma_f32_16x16x32_bf16 v[98:101], v[178:181], v[194:197], v[98:101]
	v_mfma_f32_16x16x32_bf16 v[86:89], v[170:173], v[202:205], v[86:89]
	v_mfma_f32_16x16x32_bf16 v[82:85], v[178:181], v[202:205], v[82:85]
	v_mfma_f32_16x16x32_bf16 v[70:73], v[170:173], v[210:213], v[70:73]
	v_mfma_f32_16x16x32_bf16 v[66:69], v[178:181], v[210:213], v[66:69]
	s_setprio 0
	s_barrier
	s_mov_b32 m0, s36
	v_lshl_add_u64 v[214:215], s[16:17], 0, v[132:133]
	s_add_u32 s44, s16, 0x40000
	ds_read_b128 v[182:185], v145 offset:16384
	ds_read_b128 v[186:189], v145 offset:17408
	ds_read_b128 v[190:193], v145 offset:18432
	ds_read_b128 v[194:197], v145 offset:19456
	ds_read_b128 v[198:201], v145 offset:20480
	global_load_lds_dwordx4 v132, s[16:17]
	v_lshl_add_u64 v[216:217], s[16:17], 0, v[136:137]
	s_mov_b32 m0, s37
	s_addc_u32 s45, s17, 0
	global_load_lds_dwordx4 v136, s[16:17]
	s_mov_b32 m0, s38
	v_lshl_add_u64 v[220:221], s[28:29], 0, v[134:135]
	global_load_lds_dwordx4 v132, s[44:45]
	s_mov_b32 m0, s39
	ds_read_b128 v[210:213], v145 offset:23552
	global_load_lds_dwordx4 v136, s[44:45]
	v_lshl_add_u64 v[218:219], s[28:29], 0, v[130:131]
	s_mov_b32 m0, s1
	ds_read_b128 v[206:209], v145 offset:22528
	global_load_lds_dwordx4 v130, s[28:29]
	s_mov_b32 m0, s15
	ds_read_b128 v[202:205], v145 offset:21504
	global_load_lds_dwordx4 v134, s[28:29]
	s_waitcnt vmcnt(8) lgkmcnt(0)
	s_barrier
	s_setprio 1
	v_mfma_f32_16x16x32_bf16 v[62:65], v[148:151], v[182:185], v[62:65]
	v_mfma_f32_16x16x32_bf16 v[58:61], v[158:161], v[182:185], v[58:61]
	v_mfma_f32_16x16x32_bf16 v[46:49], v[148:151], v[190:193], v[46:49]
	v_mfma_f32_16x16x32_bf16 v[42:45], v[158:161], v[190:193], v[42:45]
	v_mfma_f32_16x16x32_bf16 v[30:33], v[148:151], v[198:201], v[30:33]
	v_mfma_f32_16x16x32_bf16 v[26:29], v[158:161], v[198:201], v[26:29]
	v_mfma_f32_16x16x32_bf16 v[14:17], v[148:151], v[206:209], v[14:17]
	v_mfma_f32_16x16x32_bf16 v[10:13], v[158:161], v[206:209], v[10:13]
	v_mfma_f32_16x16x32_bf16 v[62:65], v[152:155], v[186:189], v[62:65]
	v_mfma_f32_16x16x32_bf16 v[58:61], v[162:165], v[186:189], v[58:61]
	v_mfma_f32_16x16x32_bf16 v[46:49], v[152:155], v[194:197], v[46:49]
	v_mfma_f32_16x16x32_bf16 v[42:45], v[162:165], v[194:197], v[42:45]
	v_mfma_f32_16x16x32_bf16 v[30:33], v[152:155], v[202:205], v[30:33]
	v_mfma_f32_16x16x32_bf16 v[26:29], v[162:165], v[202:205], v[26:29]
	v_mfma_f32_16x16x32_bf16 v[14:17], v[152:155], v[210:213], v[14:17]
	v_mfma_f32_16x16x32_bf16 v[10:13], v[162:165], v[210:213], v[10:13]
	s_setprio 0
	s_setprio 1
	v_mfma_f32_16x16x32_bf16 v[54:57], v[166:169], v[182:185], v[54:57]
	v_mfma_f32_16x16x32_bf16 v[50:53], v[174:177], v[182:185], v[50:53]
	v_mfma_f32_16x16x32_bf16 v[38:41], v[166:169], v[190:193], v[38:41]
	v_mfma_f32_16x16x32_bf16 v[34:37], v[174:177], v[190:193], v[34:37]
	v_mfma_f32_16x16x32_bf16 v[22:25], v[166:169], v[198:201], v[22:25]
	v_mfma_f32_16x16x32_bf16 v[18:21], v[174:177], v[198:201], v[18:21]
	v_mfma_f32_16x16x32_bf16 v[6:9], v[166:169], v[206:209], v[6:9]
	v_mfma_f32_16x16x32_bf16 v[2:5], v[174:177], v[206:209], v[2:5]
	v_mfma_f32_16x16x32_bf16 v[54:57], v[170:173], v[186:189], v[54:57]
	v_mfma_f32_16x16x32_bf16 v[50:53], v[178:181], v[186:189], v[50:53]
	v_mfma_f32_16x16x32_bf16 v[38:41], v[170:173], v[194:197], v[38:41]
	v_mfma_f32_16x16x32_bf16 v[34:37], v[178:181], v[194:197], v[34:37]
	v_mfma_f32_16x16x32_bf16 v[22:25], v[170:173], v[202:205], v[22:25]
	v_mfma_f32_16x16x32_bf16 v[18:21], v[178:181], v[202:205], v[18:21]
	v_mfma_f32_16x16x32_bf16 v[6:9], v[170:173], v[210:213], v[6:9]
	v_mfma_f32_16x16x32_bf16 v[2:5], v[178:181], v[210:213], v[2:5]
	s_setprio 0
	s_barrier
	ds_read_b128 v[148:151], v146
	ds_read_b128 v[152:155], v146 offset:1024
	ds_read_b128 v[158:161], v146 offset:2048
	ds_read_b128 v[162:165], v146 offset:3072
	ds_read_b128 v[166:169], v147
	ds_read_b128 v[170:173], v147 offset:1024
	ds_read_b128 v[174:177], v147 offset:2048
	ds_read_b128 v[178:181], v147 offset:3072
	s_add_u32 s28, s28, 0x40000
	s_addc_u32 s29, s29, 0
	s_mov_b32 m0, s20
	ds_read_b128 v[182:185], v145 offset:32768
	ds_read_b128 v[186:189], v145 offset:33792
	ds_read_b128 v[190:193], v145 offset:34816
	ds_read_b128 v[194:197], v145 offset:35840
	ds_read_b128 v[198:201], v145 offset:36864
	ds_read_b128 v[202:205], v145 offset:37888
	ds_read_b128 v[206:209], v145 offset:38912
	global_load_lds_dwordx4 v130, s[28:29]
	s_mov_b32 m0, s21
	ds_read_b128 v[210:213], v145 offset:39936
	global_load_lds_dwordx4 v134, s[28:29]
	s_waitcnt vmcnt(8) lgkmcnt(0)
	s_barrier
	s_setprio 1
	v_mfma_f32_16x16x32_bf16 v[126:129], v[148:151], v[182:185], v[126:129]
	v_mfma_f32_16x16x32_bf16 v[122:125], v[158:161], v[182:185], v[122:125]
	v_mfma_f32_16x16x32_bf16 v[110:113], v[148:151], v[190:193], v[110:113]
	v_mfma_f32_16x16x32_bf16 v[106:109], v[158:161], v[190:193], v[106:109]
	v_mfma_f32_16x16x32_bf16 v[94:97], v[148:151], v[198:201], v[94:97]
	v_mfma_f32_16x16x32_bf16 v[90:93], v[158:161], v[198:201], v[90:93]
	v_mfma_f32_16x16x32_bf16 v[78:81], v[148:151], v[206:209], v[78:81]
	v_mfma_f32_16x16x32_bf16 v[74:77], v[158:161], v[206:209], v[74:77]
	v_mfma_f32_16x16x32_bf16 v[126:129], v[152:155], v[186:189], v[126:129]
	v_mfma_f32_16x16x32_bf16 v[122:125], v[162:165], v[186:189], v[122:125]
	v_mfma_f32_16x16x32_bf16 v[110:113], v[152:155], v[194:197], v[110:113]
	v_mfma_f32_16x16x32_bf16 v[106:109], v[162:165], v[194:197], v[106:109]
	v_mfma_f32_16x16x32_bf16 v[94:97], v[152:155], v[202:205], v[94:97]
	v_mfma_f32_16x16x32_bf16 v[90:93], v[162:165], v[202:205], v[90:93]
	v_mfma_f32_16x16x32_bf16 v[78:81], v[152:155], v[210:213], v[78:81]
	v_mfma_f32_16x16x32_bf16 v[74:77], v[162:165], v[210:213], v[74:77]
	s_setprio 0
	s_setprio 1
	v_mfma_f32_16x16x32_bf16 v[118:121], v[166:169], v[182:185], v[118:121]
	v_mfma_f32_16x16x32_bf16 v[114:117], v[174:177], v[182:185], v[114:117]
	v_mfma_f32_16x16x32_bf16 v[102:105], v[166:169], v[190:193], v[102:105]
	v_mfma_f32_16x16x32_bf16 v[98:101], v[174:177], v[190:193], v[98:101]
	v_mfma_f32_16x16x32_bf16 v[86:89], v[166:169], v[198:201], v[86:89]
	v_mfma_f32_16x16x32_bf16 v[82:85], v[174:177], v[198:201], v[82:85]
	v_mfma_f32_16x16x32_bf16 v[70:73], v[166:169], v[206:209], v[70:73]
	v_mfma_f32_16x16x32_bf16 v[66:69], v[174:177], v[206:209], v[66:69]
	v_mfma_f32_16x16x32_bf16 v[118:121], v[170:173], v[186:189], v[118:121]
	v_mfma_f32_16x16x32_bf16 v[114:117], v[178:181], v[186:189], v[114:117]
	v_mfma_f32_16x16x32_bf16 v[102:105], v[170:173], v[194:197], v[102:105]
	v_mfma_f32_16x16x32_bf16 v[98:101], v[178:181], v[194:197], v[98:101]
	v_mfma_f32_16x16x32_bf16 v[86:89], v[170:173], v[202:205], v[86:89]
	v_mfma_f32_16x16x32_bf16 v[82:85], v[178:181], v[202:205], v[82:85]
	v_mfma_f32_16x16x32_bf16 v[70:73], v[170:173], v[210:213], v[70:73]
	v_mfma_f32_16x16x32_bf16 v[66:69], v[178:181], v[210:213], v[66:69]
	s_setprio 0
	s_barrier
	s_mov_b32 m0, s40
	v_lshl_add_u64 v[214:215], v[214:215], 0, s[2:3]
	s_add_u32 s16, s16, 0x40080
	ds_read_b128 v[182:185], v145 offset:49152
	ds_read_b128 v[186:189], v145 offset:50176
	ds_read_b128 v[190:193], v145 offset:51200
	ds_read_b128 v[194:197], v145 offset:52224
	global_load_lds_dwordx4 v[214:215], off
	v_lshl_add_u64 v[214:215], v[216:217], 0, s[2:3]
	s_mov_b32 m0, s41
	s_addc_u32 s17, s17, 0
	global_load_lds_dwordx4 v[214:215], off
	s_mov_b32 m0, s42
	ds_read_b128 v[210:213], v145 offset:56320
	global_load_lds_dwordx4 v132, s[16:17]
	s_mov_b32 m0, s43
	ds_read_b128 v[206:209], v145 offset:55296
	global_load_lds_dwordx4 v136, s[16:17]
	v_lshl_add_u64 v[214:215], v[218:219], 0, s[2:3]
	s_mov_b32 m0, s22
	ds_read_b128 v[202:205], v145 offset:54272
	global_load_lds_dwordx4 v[214:215], off
	v_lshl_add_u64 v[214:215], v[220:221], 0, s[2:3]
	s_mov_b32 m0, s23
	ds_read_b128 v[198:201], v145 offset:53248
	global_load_lds_dwordx4 v[214:215], off
	s_waitcnt vmcnt(8) lgkmcnt(0)
	s_barrier
	s_setprio 1
	v_mfma_f32_16x16x32_bf16 v[62:65], v[148:151], v[182:185], v[62:65]
	v_mfma_f32_16x16x32_bf16 v[58:61], v[158:161], v[182:185], v[58:61]
	v_mfma_f32_16x16x32_bf16 v[46:49], v[148:151], v[190:193], v[46:49]
	v_mfma_f32_16x16x32_bf16 v[42:45], v[158:161], v[190:193], v[42:45]
	v_mfma_f32_16x16x32_bf16 v[30:33], v[148:151], v[198:201], v[30:33]
	v_mfma_f32_16x16x32_bf16 v[26:29], v[158:161], v[198:201], v[26:29]
	v_mfma_f32_16x16x32_bf16 v[14:17], v[148:151], v[206:209], v[14:17]
	v_mfma_f32_16x16x32_bf16 v[10:13], v[158:161], v[206:209], v[10:13]
	v_mfma_f32_16x16x32_bf16 v[62:65], v[152:155], v[186:189], v[62:65]
	v_mfma_f32_16x16x32_bf16 v[58:61], v[162:165], v[186:189], v[58:61]
	v_mfma_f32_16x16x32_bf16 v[46:49], v[152:155], v[194:197], v[46:49]
	v_mfma_f32_16x16x32_bf16 v[42:45], v[162:165], v[194:197], v[42:45]
	v_mfma_f32_16x16x32_bf16 v[30:33], v[152:155], v[202:205], v[30:33]
	v_mfma_f32_16x16x32_bf16 v[26:29], v[162:165], v[202:205], v[26:29]
	v_mfma_f32_16x16x32_bf16 v[14:17], v[152:155], v[210:213], v[14:17]
	v_mfma_f32_16x16x32_bf16 v[10:13], v[162:165], v[210:213], v[10:13]
	s_setprio 0
	s_setprio 1
	v_mfma_f32_16x16x32_bf16 v[54:57], v[166:169], v[182:185], v[54:57]
	v_mfma_f32_16x16x32_bf16 v[50:53], v[174:177], v[182:185], v[50:53]
	v_mfma_f32_16x16x32_bf16 v[38:41], v[166:169], v[190:193], v[38:41]
	v_mfma_f32_16x16x32_bf16 v[34:37], v[174:177], v[190:193], v[34:37]
	v_mfma_f32_16x16x32_bf16 v[22:25], v[166:169], v[198:201], v[22:25]
	v_mfma_f32_16x16x32_bf16 v[18:21], v[174:177], v[198:201], v[18:21]
	v_mfma_f32_16x16x32_bf16 v[6:9], v[166:169], v[206:209], v[6:9]
	v_mfma_f32_16x16x32_bf16 v[2:5], v[174:177], v[206:209], v[2:5]
	v_mfma_f32_16x16x32_bf16 v[54:57], v[170:173], v[186:189], v[54:57]
	v_mfma_f32_16x16x32_bf16 v[50:53], v[178:181], v[186:189], v[50:53]
	v_mfma_f32_16x16x32_bf16 v[38:41], v[170:173], v[194:197], v[38:41]
	v_mfma_f32_16x16x32_bf16 v[34:37], v[178:181], v[194:197], v[34:37]
	v_mfma_f32_16x16x32_bf16 v[22:25], v[170:173], v[202:205], v[22:25]
	v_mfma_f32_16x16x32_bf16 v[18:21], v[178:181], v[202:205], v[18:21]
	v_mfma_f32_16x16x32_bf16 v[6:9], v[170:173], v[210:213], v[6:9]
	v_mfma_f32_16x16x32_bf16 v[2:5], v[178:181], v[210:213], v[2:5]
	s_setprio 0
	s_barrier
	s_add_i32 s33, s33, 2
	s_add_u32 s10, s10, 0x100
	s_addc_u32 s11, s11, 0
	s_cmp_gt_u32 s33, 13
	s_cbranch_scc0 .LBB0_518
	s_cmpk_lt_u32 s14, 0x100
	s_cbranch_scc0 .LBB0_521
	s_barrier

.LBB0_1250:
	ds_read_b128 v[146:149], v140
	ds_read_b128 v[150:153], v140 offset:1024
	ds_read_b128 v[154:157], v140 offset:2048
	ds_read_b128 v[158:161], v140 offset:3072
	ds_read_b128 v[162:165], v141
	ds_read_b128 v[166:169], v141 offset:1024
	ds_read_b128 v[170:173], v141 offset:2048
	ds_read_b128 v[174:177], v141 offset:3072
	s_add_u32 s14, s10, s12
	s_addc_u32 s15, s11, s13
	s_add_u32 s14, s14, 0x11400100
	s_addc_u32 s15, s15, 0
	s_add_u32 s39, s1, s12
	s_addc_u32 s40, s26, s13
	s_cmpk_eq_i32 s12, 0x700
	s_cselect_b32 s17, s9, s15
	s_cselect_b32 s16, s8, s14
	s_cselect_b32 s15, s7, s40
	s_cselect_b32 s14, s6, s39
	s_mov_b32 m0, s28
	v_lshl_add_u64 v[210:211], v[134:135], 0, s[12:13]
	ds_read_b128 v[178:181], v142
	ds_read_b128 v[182:185], v142 offset:1024
	ds_read_b128 v[186:189], v142 offset:2048
	ds_read_b128 v[190:193], v142 offset:3072
	ds_read_b128 v[194:197], v142 offset:4096
	ds_read_b128 v[198:201], v142 offset:5120
	ds_read_b128 v[202:205], v142 offset:6144
	global_load_lds_dwordx4 v[210:211], off
	v_lshl_add_u64 v[210:211], v[136:137], 0, s[12:13]
	s_mov_b32 m0, s29
	ds_read_b128 v[206:209], v142 offset:7168
	global_load_lds_dwordx4 v[210:211], off
	s_waitcnt vmcnt(8) lgkmcnt(0)
	s_barrier
	s_setprio 1
	v_mfma_f32_16x16x32_bf16 v[126:129], v[146:149], v[178:181], v[126:129]
	v_mfma_f32_16x16x32_bf16 v[122:125], v[154:157], v[178:181], v[122:125]
	v_mfma_f32_16x16x32_bf16 v[118:121], v[146:149], v[186:189], v[118:121]
	v_mfma_f32_16x16x32_bf16 v[114:117], v[154:157], v[186:189], v[114:117]
	v_mfma_f32_16x16x32_bf16 v[106:109], v[146:149], v[194:197], v[106:109]
	v_mfma_f32_16x16x32_bf16 v[98:101], v[154:157], v[194:197], v[98:101]
	v_mfma_f32_16x16x32_bf16 v[82:85], v[146:149], v[202:205], v[82:85]
	v_mfma_f32_16x16x32_bf16 v[74:77], v[154:157], v[202:205], v[74:77]
	v_mfma_f32_16x16x32_bf16 v[126:129], v[150:153], v[182:185], v[126:129]
	v_mfma_f32_16x16x32_bf16 v[122:125], v[158:161], v[182:185], v[122:125]
	v_mfma_f32_16x16x32_bf16 v[118:121], v[150:153], v[190:193], v[118:121]
	v_mfma_f32_16x16x32_bf16 v[114:117], v[158:161], v[190:193], v[114:117]
	v_mfma_f32_16x16x32_bf16 v[106:109], v[150:153], v[198:201], v[106:109]
	v_mfma_f32_16x16x32_bf16 v[98:101], v[158:161], v[198:201], v[98:101]
	v_mfma_f32_16x16x32_bf16 v[82:85], v[150:153], v[206:209], v[82:85]
	v_mfma_f32_16x16x32_bf16 v[74:77], v[158:161], v[206:209], v[74:77]
	s_setprio 0
	s_setprio 1
	v_mfma_f32_16x16x32_bf16 v[110:113], v[162:165], v[178:181], v[110:113]
	v_mfma_f32_16x16x32_bf16 v[102:105], v[170:173], v[178:181], v[102:105]
	v_mfma_f32_16x16x32_bf16 v[94:97], v[162:165], v[186:189], v[94:97]
	v_mfma_f32_16x16x32_bf16 v[90:93], v[170:173], v[186:189], v[90:93]
	v_mfma_f32_16x16x32_bf16 v[86:89], v[162:165], v[194:197], v[86:89]
	v_mfma_f32_16x16x32_bf16 v[78:81], v[170:173], v[194:197], v[78:81]
	v_mfma_f32_16x16x32_bf16 v[70:73], v[162:165], v[202:205], v[70:73]
	v_mfma_f32_16x16x32_bf16 v[66:69], v[170:173], v[202:205], v[66:69]
	v_mfma_f32_16x16x32_bf16 v[110:113], v[166:169], v[182:185], v[110:113]
	v_mfma_f32_16x16x32_bf16 v[102:105], v[174:177], v[182:185], v[102:105]
	v_mfma_f32_16x16x32_bf16 v[94:97], v[166:169], v[190:193], v[94:97]
	v_mfma_f32_16x16x32_bf16 v[90:93], v[174:177], v[190:193], v[90:93]
	v_mfma_f32_16x16x32_bf16 v[86:89], v[166:169], v[198:201], v[86:89]
	v_mfma_f32_16x16x32_bf16 v[78:81], v[174:177], v[198:201], v[78:81]
	v_mfma_f32_16x16x32_bf16 v[70:73], v[166:169], v[206:209], v[70:73]
	v_mfma_f32_16x16x32_bf16 v[66:69], v[174:177], v[206:209], v[66:69]
	s_setprio 0
	s_barrier
	s_mov_b32 m0, s30
	v_lshl_add_u64 v[210:211], s[14:15], 0, v[130:131]
	s_add_u32 s40, s14, 0x40000
	ds_read_b128 v[178:181], v142 offset:16384
	ds_read_b128 v[182:185], v142 offset:17408
	ds_read_b128 v[186:189], v142 offset:18432
	ds_read_b128 v[190:193], v142 offset:19456
	ds_read_b128 v[194:197], v142 offset:20480
	global_load_lds_dwordx4 v130, s[14:15]
	v_lshl_add_u64 v[212:213], s[14:15], 0, v[132:133]
	s_mov_b32 m0, s31
	s_addc_u32 s41, s15, 0
	global_load_lds_dwordx4 v132, s[14:15]
	s_mov_b32 m0, s33
	v_lshl_add_u64 v[216:217], s[16:17], 0, v[132:133]
	global_load_lds_dwordx4 v130, s[40:41]
	s_mov_b32 m0, s34
	ds_read_b128 v[206:209], v142 offset:23552
	global_load_lds_dwordx4 v132, s[40:41]
	v_lshl_add_u64 v[214:215], s[16:17], 0, v[130:131]
	s_mov_b32 m0, s5
	ds_read_b128 v[202:205], v142 offset:22528
	global_load_lds_dwordx4 v130, s[16:17]
	s_mov_b32 m0, s21
	ds_read_b128 v[198:201], v142 offset:21504
	global_load_lds_dwordx4 v132, s[16:17]
	s_waitcnt vmcnt(8) lgkmcnt(0)
	s_barrier
	s_setprio 1
	v_mfma_f32_16x16x32_bf16 v[62:65], v[146:149], v[178:181], v[62:65]
	v_mfma_f32_16x16x32_bf16 v[58:61], v[154:157], v[178:181], v[58:61]
	v_mfma_f32_16x16x32_bf16 v[54:57], v[146:149], v[186:189], v[54:57]
	v_mfma_f32_16x16x32_bf16 v[50:53], v[154:157], v[186:189], v[50:53]
	v_mfma_f32_16x16x32_bf16 v[34:37], v[146:149], v[194:197], v[34:37]
	v_mfma_f32_16x16x32_bf16 v[26:29], v[154:157], v[194:197], v[26:29]
	v_mfma_f32_16x16x32_bf16 v[22:25], v[146:149], v[202:205], v[22:25]
	v_mfma_f32_16x16x32_bf16 v[10:13], v[154:157], v[202:205], v[10:13]
	v_mfma_f32_16x16x32_bf16 v[62:65], v[150:153], v[182:185], v[62:65]
	v_mfma_f32_16x16x32_bf16 v[58:61], v[158:161], v[182:185], v[58:61]
	v_mfma_f32_16x16x32_bf16 v[54:57], v[150:153], v[190:193], v[54:57]
	v_mfma_f32_16x16x32_bf16 v[50:53], v[158:161], v[190:193], v[50:53]
	v_mfma_f32_16x16x32_bf16 v[34:37], v[150:153], v[198:201], v[34:37]
	v_mfma_f32_16x16x32_bf16 v[26:29], v[158:161], v[198:201], v[26:29]
	v_mfma_f32_16x16x32_bf16 v[22:25], v[150:153], v[206:209], v[22:25]
	v_mfma_f32_16x16x32_bf16 v[10:13], v[158:161], v[206:209], v[10:13]
	s_setprio 0
	s_setprio 1
	v_mfma_f32_16x16x32_bf16 v[46:49], v[162:165], v[178:181], v[46:49]
	v_mfma_f32_16x16x32_bf16 v[42:45], v[170:173], v[178:181], v[42:45]
	v_mfma_f32_16x16x32_bf16 v[38:41], v[162:165], v[186:189], v[38:41]
	v_mfma_f32_16x16x32_bf16 v[30:33], v[170:173], v[186:189], v[30:33]
	v_mfma_f32_16x16x32_bf16 v[18:21], v[162:165], v[194:197], v[18:21]
	v_mfma_f32_16x16x32_bf16 v[14:17], v[170:173], v[194:197], v[14:17]
	v_mfma_f32_16x16x32_bf16 v[6:9], v[162:165], v[202:205], v[6:9]
	v_mfma_f32_16x16x32_bf16 v[2:5], v[170:173], v[202:205], v[2:5]
	v_mfma_f32_16x16x32_bf16 v[46:49], v[166:169], v[182:185], v[46:49]
	v_mfma_f32_16x16x32_bf16 v[42:45], v[174:177], v[182:185], v[42:45]
	v_mfma_f32_16x16x32_bf16 v[38:41], v[166:169], v[190:193], v[38:41]
	v_mfma_f32_16x16x32_bf16 v[30:33], v[174:177], v[190:193], v[30:33]
	v_mfma_f32_16x16x32_bf16 v[18:21], v[166:169], v[198:201], v[18:21]
	v_mfma_f32_16x16x32_bf16 v[14:17], v[174:177], v[198:201], v[14:17]
	v_mfma_f32_16x16x32_bf16 v[6:9], v[166:169], v[206:209], v[6:9]
	v_mfma_f32_16x16x32_bf16 v[2:5], v[174:177], v[206:209], v[2:5]
	s_setprio 0
	s_barrier
	ds_read_b128 v[146:149], v143
	ds_read_b128 v[150:153], v143 offset:1024
	ds_read_b128 v[154:157], v143 offset:2048
	ds_read_b128 v[158:161], v143 offset:3072
	ds_read_b128 v[162:165], v144
	ds_read_b128 v[166:169], v144 offset:1024
	ds_read_b128 v[170:173], v144 offset:2048
	ds_read_b128 v[174:177], v144 offset:3072
	s_add_u32 s16, s16, 0x40000
	s_addc_u32 s17, s17, 0
	s_mov_b32 m0, s22
	ds_read_b128 v[178:181], v142 offset:32768
	ds_read_b128 v[182:185], v142 offset:33792
	ds_read_b128 v[186:189], v142 offset:34816
	ds_read_b128 v[190:193], v142 offset:35840
	ds_read_b128 v[194:197], v142 offset:36864
	ds_read_b128 v[198:201], v142 offset:37888
	ds_read_b128 v[202:205], v142 offset:38912
	global_load_lds_dwordx4 v130, s[16:17]
	s_mov_b32 m0, s23
	ds_read_b128 v[206:209], v142 offset:39936
	global_load_lds_dwordx4 v132, s[16:17]
	s_waitcnt vmcnt(8) lgkmcnt(0)
	s_barrier
	s_setprio 1
	v_mfma_f32_16x16x32_bf16 v[126:129], v[146:149], v[178:181], v[126:129]
	v_mfma_f32_16x16x32_bf16 v[122:125], v[154:157], v[178:181], v[122:125]
	v_mfma_f32_16x16x32_bf16 v[118:121], v[146:149], v[186:189], v[118:121]
	v_mfma_f32_16x16x32_bf16 v[114:117], v[154:157], v[186:189], v[114:117]
	v_mfma_f32_16x16x32_bf16 v[106:109], v[146:149], v[194:197], v[106:109]
	v_mfma_f32_16x16x32_bf16 v[98:101], v[154:157], v[194:197], v[98:101]
	v_mfma_f32_16x16x32_bf16 v[82:85], v[146:149], v[202:205], v[82:85]
	v_mfma_f32_16x16x32_bf16 v[74:77], v[154:157], v[202:205], v[74:77]
	v_mfma_f32_16x16x32_bf16 v[126:129], v[150:153], v[182:185], v[126:129]
	v_mfma_f32_16x16x32_bf16 v[122:125], v[158:161], v[182:185], v[122:125]
	v_mfma_f32_16x16x32_bf16 v[118:121], v[150:153], v[190:193], v[118:121]
	v_mfma_f32_16x16x32_bf16 v[114:117], v[158:161], v[190:193], v[114:117]
	v_mfma_f32_16x16x32_bf16 v[106:109], v[150:153], v[198:201], v[106:109]
	v_mfma_f32_16x16x32_bf16 v[98:101], v[158:161], v[198:201], v[98:101]
	v_mfma_f32_16x16x32_bf16 v[82:85], v[150:153], v[206:209], v[82:85]
	v_mfma_f32_16x16x32_bf16 v[74:77], v[158:161], v[206:209], v[74:77]
	s_setprio 0
	s_setprio 1
	v_mfma_f32_16x16x32_bf16 v[110:113], v[162:165], v[178:181], v[110:113]
	v_mfma_f32_16x16x32_bf16 v[102:105], v[170:173], v[178:181], v[102:105]
	v_mfma_f32_16x16x32_bf16 v[94:97], v[162:165], v[186:189], v[94:97]
	v_mfma_f32_16x16x32_bf16 v[90:93], v[170:173], v[186:189], v[90:93]
	v_mfma_f32_16x16x32_bf16 v[86:89], v[162:165], v[194:197], v[86:89]
	v_mfma_f32_16x16x32_bf16 v[78:81], v[170:173], v[194:197], v[78:81]
	v_mfma_f32_16x16x32_bf16 v[70:73], v[162:165], v[202:205], v[70:73]
	v_mfma_f32_16x16x32_bf16 v[66:69], v[170:173], v[202:205], v[66:69]
	v_mfma_f32_16x16x32_bf16 v[110:113], v[166:169], v[182:185], v[110:113]
	v_mfma_f32_16x16x32_bf16 v[102:105], v[174:177], v[182:185], v[102:105]
	v_mfma_f32_16x16x32_bf16 v[94:97], v[166:169], v[190:193], v[94:97]
	v_mfma_f32_16x16x32_bf16 v[90:93], v[174:177], v[190:193], v[90:93]
	v_mfma_f32_16x16x32_bf16 v[86:89], v[166:169], v[198:201], v[86:89]
	v_mfma_f32_16x16x32_bf16 v[78:81], v[174:177], v[198:201], v[78:81]
	v_mfma_f32_16x16x32_bf16 v[70:73], v[166:169], v[206:209], v[70:73]
	v_mfma_f32_16x16x32_bf16 v[66:69], v[174:177], v[206:209], v[66:69]
	s_setprio 0
	s_barrier
	s_mov_b32 m0, s35
	v_lshl_add_u64 v[210:211], v[210:211], 0, s[2:3]
	s_add_u32 s14, s14, 0x40080
	ds_read_b128 v[178:181], v142 offset:49152
	ds_read_b128 v[182:185], v142 offset:50176
	ds_read_b128 v[186:189], v142 offset:51200
	ds_read_b128 v[190:193], v142 offset:52224
	global_load_lds_dwordx4 v[210:211], off
	v_lshl_add_u64 v[210:211], v[212:213], 0, s[2:3]
	s_mov_b32 m0, s36
	s_addc_u32 s15, s15, 0
	global_load_lds_dwordx4 v[210:211], off
	s_mov_b32 m0, s37
	ds_read_b128 v[206:209], v142 offset:56320
	global_load_lds_dwordx4 v130, s[14:15]
	s_mov_b32 m0, s38
	ds_read_b128 v[202:205], v142 offset:55296
	global_load_lds_dwordx4 v132, s[14:15]
	v_lshl_add_u64 v[210:211], v[214:215], 0, s[2:3]
	s_mov_b32 m0, s24
	ds_read_b128 v[198:201], v142 offset:54272
	global_load_lds_dwordx4 v[210:211], off
	v_lshl_add_u64 v[210:211], v[216:217], 0, s[2:3]
	s_mov_b32 m0, s25
	ds_read_b128 v[194:197], v142 offset:53248
	global_load_lds_dwordx4 v[210:211], off
	s_waitcnt vmcnt(8) lgkmcnt(0)
	s_barrier
	s_setprio 1
	v_mfma_f32_16x16x32_bf16 v[62:65], v[146:149], v[178:181], v[62:65]
	v_mfma_f32_16x16x32_bf16 v[58:61], v[154:157], v[178:181], v[58:61]
	v_mfma_f32_16x16x32_bf16 v[54:57], v[146:149], v[186:189], v[54:57]
	v_mfma_f32_16x16x32_bf16 v[50:53], v[154:157], v[186:189], v[50:53]
	v_mfma_f32_16x16x32_bf16 v[34:37], v[146:149], v[194:197], v[34:37]
	v_mfma_f32_16x16x32_bf16 v[26:29], v[154:157], v[194:197], v[26:29]
	v_mfma_f32_16x16x32_bf16 v[22:25], v[146:149], v[202:205], v[22:25]
	v_mfma_f32_16x16x32_bf16 v[10:13], v[154:157], v[202:205], v[10:13]
	v_mfma_f32_16x16x32_bf16 v[62:65], v[150:153], v[182:185], v[62:65]
	v_mfma_f32_16x16x32_bf16 v[58:61], v[158:161], v[182:185], v[58:61]
	v_mfma_f32_16x16x32_bf16 v[54:57], v[150:153], v[190:193], v[54:57]
	v_mfma_f32_16x16x32_bf16 v[50:53], v[158:161], v[190:193], v[50:53]
	v_mfma_f32_16x16x32_bf16 v[34:37], v[150:153], v[198:201], v[34:37]
	v_mfma_f32_16x16x32_bf16 v[26:29], v[158:161], v[198:201], v[26:29]
	v_mfma_f32_16x16x32_bf16 v[22:25], v[150:153], v[206:209], v[22:25]
	v_mfma_f32_16x16x32_bf16 v[10:13], v[158:161], v[206:209], v[10:13]
	s_setprio 0
	s_setprio 1
	v_mfma_f32_16x16x32_bf16 v[46:49], v[162:165], v[178:181], v[46:49]
	v_mfma_f32_16x16x32_bf16 v[42:45], v[170:173], v[178:181], v[42:45]
	v_mfma_f32_16x16x32_bf16 v[38:41], v[162:165], v[186:189], v[38:41]
	v_mfma_f32_16x16x32_bf16 v[30:33], v[170:173], v[186:189], v[30:33]
	v_mfma_f32_16x16x32_bf16 v[18:21], v[162:165], v[194:197], v[18:21]
	v_mfma_f32_16x16x32_bf16 v[14:17], v[170:173], v[194:197], v[14:17]
	v_mfma_f32_16x16x32_bf16 v[6:9], v[162:165], v[202:205], v[6:9]
	v_mfma_f32_16x16x32_bf16 v[2:5], v[170:173], v[202:205], v[2:5]
	v_mfma_f32_16x16x32_bf16 v[46:49], v[166:169], v[182:185], v[46:49]
	v_mfma_f32_16x16x32_bf16 v[42:45], v[174:177], v[182:185], v[42:45]
	v_mfma_f32_16x16x32_bf16 v[38:41], v[166:169], v[190:193], v[38:41]
	v_mfma_f32_16x16x32_bf16 v[30:33], v[174:177], v[190:193], v[30:33]
	v_mfma_f32_16x16x32_bf16 v[18:21], v[166:169], v[198:201], v[18:21]
	v_mfma_f32_16x16x32_bf16 v[14:17], v[174:177], v[198:201], v[14:17]
	v_mfma_f32_16x16x32_bf16 v[6:9], v[166:169], v[206:209], v[6:9]
	v_mfma_f32_16x16x32_bf16 v[2:5], v[174:177], v[206:209], v[2:5]
	s_setprio 0
	s_barrier
	s_add_i32 s27, s27, 2
	s_add_u32 s12, s12, 0x100
	s_addc_u32 s13, s13, 0
	s_cmp_gt_u32 s27, 13
	s_cbranch_scc0 .LBB0_1250
	s_cmpk_lt_u32 s19, 0x100
	s_cbranch_scc0 .LBB0_1253
	s_barrier

.LBB0_1381:
	ds_read_b128 v[138:141], v147
	ds_read_b128 v[150:153], v147 offset:1024
	ds_read_b128 v[154:157], v147 offset:2048
	ds_read_b128 v[158:161], v147 offset:3072
	ds_read_b128 v[162:165], v148
	ds_read_b128 v[166:169], v148 offset:1024
	ds_read_b128 v[170:173], v148 offset:2048
	ds_read_b128 v[174:177], v148 offset:3072
	s_add_u32 s24, s2, 0xfffc0080
	s_addc_u32 s25, s3, -1
	s_cmp_eq_u32 s53, 12
	s_cselect_b32 s27, s17, s25
	s_cselect_b32 s26, s49, s24
	s_cselect_b32 s25, s15, s52
	s_cselect_b32 s24, s50, s51
	s_add_i32 m0, s23, 0xc000
	ds_read_b128 v[178:181], v149
	ds_read_b128 v[182:185], v149 offset:1024
	ds_read_b128 v[186:189], v149 offset:2048
	ds_read_b128 v[190:193], v149 offset:3072
	ds_read_b128 v[194:197], v149 offset:4096
	ds_read_b128 v[198:201], v149 offset:5120
	ds_read_b128 v[202:205], v149 offset:6144
	global_load_lds_dwordx4 v132, s[2:3]
	s_add_i32 m0, s23, 0xe000
	ds_read_b128 v[206:209], v149 offset:7168
	global_load_lds_dwordx4 v134, s[2:3]
	s_waitcnt vmcnt(8) lgkmcnt(0)
	s_barrier
	s_setprio 1
	v_mfma_f32_16x16x32_bf16 v[124:127], v[138:141], v[178:181], v[124:127]
	v_mfma_f32_16x16x32_bf16 v[120:123], v[154:157], v[178:181], v[120:123]
	v_mfma_f32_16x16x32_bf16 v[116:119], v[138:141], v[186:189], v[116:119]
	v_mfma_f32_16x16x32_bf16 v[112:115], v[154:157], v[186:189], v[112:115]
	v_mfma_f32_16x16x32_bf16 v[104:107], v[138:141], v[194:197], v[104:107]
	v_mfma_f32_16x16x32_bf16 v[96:99], v[154:157], v[194:197], v[96:99]
	v_mfma_f32_16x16x32_bf16 v[88:91], v[138:141], v[202:205], v[88:91]
	v_mfma_f32_16x16x32_bf16 v[80:83], v[154:157], v[202:205], v[80:83]
	v_mfma_f32_16x16x32_bf16 v[124:127], v[150:153], v[182:185], v[124:127]
	v_mfma_f32_16x16x32_bf16 v[120:123], v[158:161], v[182:185], v[120:123]
	v_mfma_f32_16x16x32_bf16 v[116:119], v[150:153], v[190:193], v[116:119]
	v_mfma_f32_16x16x32_bf16 v[112:115], v[158:161], v[190:193], v[112:115]
	v_mfma_f32_16x16x32_bf16 v[104:107], v[150:153], v[198:201], v[104:107]
	v_mfma_f32_16x16x32_bf16 v[96:99], v[158:161], v[198:201], v[96:99]
	v_mfma_f32_16x16x32_bf16 v[88:91], v[150:153], v[206:209], v[88:91]
	v_mfma_f32_16x16x32_bf16 v[80:83], v[158:161], v[206:209], v[80:83]
	s_setprio 0
	s_setprio 1
	v_mfma_f32_16x16x32_bf16 v[108:111], v[162:165], v[178:181], v[108:111]
	v_mfma_f32_16x16x32_bf16 v[100:103], v[170:173], v[178:181], v[100:103]
	v_mfma_f32_16x16x32_bf16 v[92:95], v[162:165], v[186:189], v[92:95]
	v_mfma_f32_16x16x32_bf16 v[84:87], v[170:173], v[186:189], v[84:87]
	v_mfma_f32_16x16x32_bf16 v[76:79], v[162:165], v[194:197], v[76:79]
	v_mfma_f32_16x16x32_bf16 v[72:75], v[170:173], v[194:197], v[72:75]
	v_mfma_f32_16x16x32_bf16 v[68:71], v[162:165], v[202:205], v[68:71]
	v_mfma_f32_16x16x32_bf16 v[64:67], v[170:173], v[202:205], v[64:67]
	v_mfma_f32_16x16x32_bf16 v[108:111], v[166:169], v[182:185], v[108:111]
	v_mfma_f32_16x16x32_bf16 v[100:103], v[174:177], v[182:185], v[100:103]
	v_mfma_f32_16x16x32_bf16 v[92:95], v[166:169], v[190:193], v[92:95]
	v_mfma_f32_16x16x32_bf16 v[84:87], v[174:177], v[190:193], v[84:87]
	v_mfma_f32_16x16x32_bf16 v[76:79], v[166:169], v[198:201], v[76:79]
	v_mfma_f32_16x16x32_bf16 v[72:75], v[174:177], v[198:201], v[72:75]
	v_mfma_f32_16x16x32_bf16 v[68:71], v[166:169], v[206:209], v[68:71]
	v_mfma_f32_16x16x32_bf16 v[64:67], v[174:177], v[206:209], v[64:67]
	s_setprio 0
	s_barrier
	s_add_i32 s54, s4, s29
	s_mov_b32 m0, s54
	ds_read_b128 v[178:181], v149 offset:16384
	ds_read_b128 v[182:185], v149 offset:17408
	ds_read_b128 v[186:189], v149 offset:18432
	ds_read_b128 v[190:193], v149 offset:19456
	ds_read_b128 v[194:197], v149 offset:20480
	global_load_lds_dwordx4 v130, s[24:25]
	s_add_i32 m0, s54, 0x2000
	s_add_u32 s54, s24, 0x40000
	s_addc_u32 s55, s25, 0
	s_add_i32 s56, s41, s29
	global_load_lds_dwordx4 v128, s[24:25]
	s_mov_b32 m0, s56
	v_lshl_add_u64 v[214:215], s[26:27], 0, v[128:129]
	global_load_lds_dwordx4 v130, s[54:55]
	s_add_i32 m0, s56, 0x2000
	ds_read_b128 v[206:209], v149 offset:23552
	global_load_lds_dwordx4 v128, s[54:55]
	v_lshl_add_u64 v[212:213], s[26:27], 0, v[130:131]
	s_mov_b32 m0, s23
	ds_read_b128 v[202:205], v149 offset:22528
	global_load_lds_dwordx4 v130, s[26:27]
	s_mov_b32 m0, s34
	ds_read_b128 v[198:201], v149 offset:21504
	global_load_lds_dwordx4 v128, s[26:27]
	s_waitcnt vmcnt(8) lgkmcnt(0)
	s_barrier
	s_setprio 1
	v_mfma_f32_16x16x32_bf16 v[60:63], v[138:141], v[178:181], v[60:63]
	v_mfma_f32_16x16x32_bf16 v[56:59], v[154:157], v[178:181], v[56:59]
	v_mfma_f32_16x16x32_bf16 v[52:55], v[138:141], v[186:189], v[52:55]
	v_mfma_f32_16x16x32_bf16 v[48:51], v[154:157], v[186:189], v[48:51]
	v_mfma_f32_16x16x32_bf16 v[44:47], v[138:141], v[194:197], v[44:47]
	v_mfma_f32_16x16x32_bf16 v[32:35], v[154:157], v[194:197], v[32:35]
	v_mfma_f32_16x16x32_bf16 v[20:23], v[138:141], v[202:205], v[20:23]
	v_mfma_f32_16x16x32_bf16 v[8:11], v[154:157], v[202:205], v[8:11]
	v_mfma_f32_16x16x32_bf16 v[60:63], v[150:153], v[182:185], v[60:63]
	v_mfma_f32_16x16x32_bf16 v[56:59], v[158:161], v[182:185], v[56:59]
	v_mfma_f32_16x16x32_bf16 v[52:55], v[150:153], v[190:193], v[52:55]
	v_mfma_f32_16x16x32_bf16 v[48:51], v[158:161], v[190:193], v[48:51]
	v_mfma_f32_16x16x32_bf16 v[44:47], v[150:153], v[198:201], v[44:47]
	v_mfma_f32_16x16x32_bf16 v[32:35], v[158:161], v[198:201], v[32:35]
	v_mfma_f32_16x16x32_bf16 v[20:23], v[150:153], v[206:209], v[20:23]
	v_mfma_f32_16x16x32_bf16 v[8:11], v[158:161], v[206:209], v[8:11]
	s_setprio 0
	s_setprio 1
	v_mfma_f32_16x16x32_bf16 v[40:43], v[162:165], v[178:181], v[40:43]
	v_mfma_f32_16x16x32_bf16 v[36:39], v[170:173], v[178:181], v[36:39]
	v_mfma_f32_16x16x32_bf16 v[28:31], v[162:165], v[186:189], v[28:31]
	v_mfma_f32_16x16x32_bf16 v[24:27], v[170:173], v[186:189], v[24:27]
	v_mfma_f32_16x16x32_bf16 v[16:19], v[162:165], v[194:197], v[16:19]
	v_mfma_f32_16x16x32_bf16 v[12:15], v[170:173], v[194:197], v[12:15]
	v_mfma_f32_16x16x32_bf16 v[4:7], v[162:165], v[202:205], v[4:7]
	v_mfma_f32_16x16x32_bf16 v[0:3], v[170:173], v[202:205], v[0:3]
	v_mfma_f32_16x16x32_bf16 v[40:43], v[166:169], v[182:185], v[40:43]
	v_mfma_f32_16x16x32_bf16 v[36:39], v[174:177], v[182:185], v[36:39]
	v_mfma_f32_16x16x32_bf16 v[28:31], v[166:169], v[190:193], v[28:31]
	v_mfma_f32_16x16x32_bf16 v[24:27], v[174:177], v[190:193], v[24:27]
	v_mfma_f32_16x16x32_bf16 v[16:19], v[166:169], v[198:201], v[16:19]
	v_mfma_f32_16x16x32_bf16 v[12:15], v[174:177], v[198:201], v[12:15]
	v_mfma_f32_16x16x32_bf16 v[4:7], v[166:169], v[206:209], v[4:7]
	v_mfma_f32_16x16x32_bf16 v[0:3], v[174:177], v[206:209], v[0:3]
	s_setprio 0
	s_barrier
	s_add_i32 s54, 0, 0x18000
	s_add_i32 s55, 0, 0x1c000
	v_add_u32_e32 v158, s54, v145
	v_add_u32_e32 v174, s55, v145
	ds_read_b128 v[138:141], v158
	ds_read_b128 v[150:153], v158 offset:1024
	ds_read_b128 v[154:157], v158 offset:2048
	ds_read_b128 v[158:161], v158 offset:3072
	ds_read_b128 v[162:165], v174
	ds_read_b128 v[166:169], v174 offset:1024
	ds_read_b128 v[170:173], v174 offset:2048
	ds_read_b128 v[174:177], v174 offset:3072
	s_add_u32 s26, s26, 0x40000
	s_addc_u32 s27, s27, 0
	s_mov_b32 m0, s35
	ds_read_b128 v[178:181], v149 offset:32768
	ds_read_b128 v[182:185], v149 offset:33792
	ds_read_b128 v[186:189], v149 offset:34816
	ds_read_b128 v[190:193], v149 offset:35840
	ds_read_b128 v[194:197], v149 offset:36864
	ds_read_b128 v[198:201], v149 offset:37888
	ds_read_b128 v[202:205], v149 offset:38912
	global_load_lds_dwordx4 v130, s[26:27]
	s_mov_b32 m0, s36
	ds_read_b128 v[206:209], v149 offset:39936
	global_load_lds_dwordx4 v128, s[26:27]
	s_waitcnt vmcnt(8) lgkmcnt(0)
	s_barrier
	s_setprio 1
	v_mfma_f32_16x16x32_bf16 v[124:127], v[138:141], v[178:181], v[124:127]
	v_mfma_f32_16x16x32_bf16 v[120:123], v[154:157], v[178:181], v[120:123]
	v_mfma_f32_16x16x32_bf16 v[116:119], v[138:141], v[186:189], v[116:119]
	v_mfma_f32_16x16x32_bf16 v[112:115], v[154:157], v[186:189], v[112:115]
	v_mfma_f32_16x16x32_bf16 v[104:107], v[138:141], v[194:197], v[104:107]
	v_mfma_f32_16x16x32_bf16 v[96:99], v[154:157], v[194:197], v[96:99]
	v_mfma_f32_16x16x32_bf16 v[88:91], v[138:141], v[202:205], v[88:91]
	v_mfma_f32_16x16x32_bf16 v[80:83], v[154:157], v[202:205], v[80:83]
	v_mfma_f32_16x16x32_bf16 v[124:127], v[150:153], v[182:185], v[124:127]
	v_mfma_f32_16x16x32_bf16 v[120:123], v[158:161], v[182:185], v[120:123]
	v_mfma_f32_16x16x32_bf16 v[116:119], v[150:153], v[190:193], v[116:119]
	v_mfma_f32_16x16x32_bf16 v[112:115], v[158:161], v[190:193], v[112:115]
	v_mfma_f32_16x16x32_bf16 v[104:107], v[150:153], v[198:201], v[104:107]
	v_mfma_f32_16x16x32_bf16 v[96:99], v[158:161], v[198:201], v[96:99]
	v_mfma_f32_16x16x32_bf16 v[88:91], v[150:153], v[206:209], v[88:91]
	v_mfma_f32_16x16x32_bf16 v[80:83], v[158:161], v[206:209], v[80:83]
	s_setprio 0
	s_setprio 1
	v_mfma_f32_16x16x32_bf16 v[108:111], v[162:165], v[178:181], v[108:111]
	v_mfma_f32_16x16x32_bf16 v[100:103], v[170:173], v[178:181], v[100:103]
	v_mfma_f32_16x16x32_bf16 v[92:95], v[162:165], v[186:189], v[92:95]
	v_mfma_f32_16x16x32_bf16 v[84:87], v[170:173], v[186:189], v[84:87]
	v_mfma_f32_16x16x32_bf16 v[76:79], v[162:165], v[194:197], v[76:79]
	v_mfma_f32_16x16x32_bf16 v[72:75], v[170:173], v[194:197], v[72:75]
	v_mfma_f32_16x16x32_bf16 v[68:71], v[162:165], v[202:205], v[68:71]
	v_mfma_f32_16x16x32_bf16 v[64:67], v[170:173], v[202:205], v[64:67]
	v_mfma_f32_16x16x32_bf16 v[108:111], v[166:169], v[182:185], v[108:111]
	v_mfma_f32_16x16x32_bf16 v[100:103], v[174:177], v[182:185], v[100:103]
	v_mfma_f32_16x16x32_bf16 v[92:95], v[166:169], v[190:193], v[92:95]
	v_mfma_f32_16x16x32_bf16 v[84:87], v[174:177], v[190:193], v[84:87]
	v_mfma_f32_16x16x32_bf16 v[76:79], v[166:169], v[198:201], v[76:79]
	v_mfma_f32_16x16x32_bf16 v[72:75], v[174:177], v[198:201], v[72:75]
	v_mfma_f32_16x16x32_bf16 v[68:71], v[166:169], v[206:209], v[68:71]
	v_mfma_f32_16x16x32_bf16 v[64:67], v[174:177], v[206:209], v[64:67]
	s_setprio 0
	s_barrier
	s_add_i32 s26, s54, s29
	s_add_i32 m0, s26, 0xffffff80
	ds_read_b128 v[178:181], v149 offset:49152
	ds_read_b128 v[182:185], v149 offset:50176
	ds_read_b128 v[186:189], v149 offset:51200
	ds_read_b128 v[190:193], v149 offset:52224
	global_load_lds_dwordx4 v130, s[24:25] offset:128
	s_add_i32 m0, s26, 0x1f80
	s_add_i32 s26, s55, s29
	global_load_lds_dwordx4 v128, s[24:25] offset:128
	s_add_u32 s24, s24, 0x40080
	s_addc_u32 s25, s25, 0
	s_mov_b32 m0, s26
	ds_read_b128 v[206:209], v149 offset:56320
	global_load_lds_dwordx4 v130, s[24:25]
	s_add_i32 m0, s26, 0x2000
	ds_read_b128 v[202:205], v149 offset:55296
	global_load_lds_dwordx4 v128, s[24:25]
	v_lshl_add_u64 v[142:143], v[212:213], 0, s[8:9]
	s_mov_b32 m0, s38
	ds_read_b128 v[198:201], v149 offset:54272
	global_load_lds_dwordx4 v[142:143], off
	v_lshl_add_u64 v[142:143], v[214:215], 0, s[8:9]
	s_mov_b32 m0, s39
	ds_read_b128 v[194:197], v149 offset:53248
	global_load_lds_dwordx4 v[142:143], off
	s_waitcnt vmcnt(8) lgkmcnt(0)
	s_barrier
	s_setprio 1
	v_mfma_f32_16x16x32_bf16 v[60:63], v[138:141], v[178:181], v[60:63]
	v_mfma_f32_16x16x32_bf16 v[56:59], v[154:157], v[178:181], v[56:59]
	v_mfma_f32_16x16x32_bf16 v[52:55], v[138:141], v[186:189], v[52:55]
	v_mfma_f32_16x16x32_bf16 v[48:51], v[154:157], v[186:189], v[48:51]
	v_mfma_f32_16x16x32_bf16 v[44:47], v[138:141], v[194:197], v[44:47]
	v_mfma_f32_16x16x32_bf16 v[32:35], v[154:157], v[194:197], v[32:35]
	v_mfma_f32_16x16x32_bf16 v[20:23], v[138:141], v[202:205], v[20:23]
	v_mfma_f32_16x16x32_bf16 v[8:11], v[154:157], v[202:205], v[8:11]
	v_mfma_f32_16x16x32_bf16 v[60:63], v[150:153], v[182:185], v[60:63]
	v_mfma_f32_16x16x32_bf16 v[56:59], v[158:161], v[182:185], v[56:59]
	v_mfma_f32_16x16x32_bf16 v[52:55], v[150:153], v[190:193], v[52:55]
	v_mfma_f32_16x16x32_bf16 v[48:51], v[158:161], v[190:193], v[48:51]
	v_mfma_f32_16x16x32_bf16 v[44:47], v[150:153], v[198:201], v[44:47]
	v_mfma_f32_16x16x32_bf16 v[32:35], v[158:161], v[198:201], v[32:35]
	v_mfma_f32_16x16x32_bf16 v[20:23], v[150:153], v[206:209], v[20:23]
	v_mfma_f32_16x16x32_bf16 v[8:11], v[158:161], v[206:209], v[8:11]
	s_setprio 0
	s_setprio 1
	v_mfma_f32_16x16x32_bf16 v[40:43], v[162:165], v[178:181], v[40:43]
	v_mfma_f32_16x16x32_bf16 v[36:39], v[170:173], v[178:181], v[36:39]
	v_mfma_f32_16x16x32_bf16 v[28:31], v[162:165], v[186:189], v[28:31]
	v_mfma_f32_16x16x32_bf16 v[24:27], v[170:173], v[186:189], v[24:27]
	v_mfma_f32_16x16x32_bf16 v[16:19], v[162:165], v[194:197], v[16:19]
	v_mfma_f32_16x16x32_bf16 v[12:15], v[170:173], v[194:197], v[12:15]
	v_mfma_f32_16x16x32_bf16 v[4:7], v[162:165], v[202:205], v[4:7]
	v_mfma_f32_16x16x32_bf16 v[0:3], v[170:173], v[202:205], v[0:3]
	v_mfma_f32_16x16x32_bf16 v[40:43], v[166:169], v[182:185], v[40:43]
	v_mfma_f32_16x16x32_bf16 v[36:39], v[174:177], v[182:185], v[36:39]
	v_mfma_f32_16x16x32_bf16 v[28:31], v[166:169], v[190:193], v[28:31]
	v_mfma_f32_16x16x32_bf16 v[24:27], v[174:177], v[190:193], v[24:27]
	v_mfma_f32_16x16x32_bf16 v[16:19], v[166:169], v[198:201], v[16:19]
	v_mfma_f32_16x16x32_bf16 v[12:15], v[174:177], v[198:201], v[12:15]
	v_mfma_f32_16x16x32_bf16 v[4:7], v[166:169], v[206:209], v[4:7]
	v_mfma_f32_16x16x32_bf16 v[0:3], v[174:177], v[206:209], v[0:3]
	s_setprio 0
	s_barrier
	s_add_i32 s53, s53, 2
	s_add_u32 s2, s2, 0x100
	s_addc_u32 s3, s3, 0
	s_add_u32 s51, s51, 0x100
	s_addc_u32 s52, s52, 0
	s_cmp_gt_u32 s53, 13
	s_cbranch_scc0 .LBB0_1381
	s_and_b64 vcc, exec, s[10:11]
	s_cbranch_vccz .LBB0_1384
	s_barrier
